# P0: pre-touch the w_in tiles of later transpose loop trips
# speedup vs baseline: 1.0022x; 1.0022x over previous
; __device__ __forceinline__ void tr_tile(const float* W, int K, int N, int kt, int nt, LAS float* tile, const float* kscale, h16* dst, int mode, h16* dstG) {
;     const int tid = threadIdx.x, k0 = kt * 64, n0 = nt * 64;
;     {
;         const int kr = tid >> 4, nc = (tid & 15) * 4;
; #pragma unroll
;         for (int i = 0; i < 2; ++i) {
;             const int k = kr + 32 * i;
;             f32x4 v = {0.f, 0.f, 0.f, 0.f};
;             if (n0 + nc < N) v = *(const f32x4*)(W + (size_t)(k0 + k) * N + n0 + nc);
; __device__ __forceinline__ void p0_prep(const Params& p, LAS unsigned char* lds) {
;     ...
;     constexpr int I_IN = 16 * 61, I_LW = 8, I_LA = 8, I_LG = 16;
;     constexpr int NIT = I_IN + I_LW + I_LA + I_LG;
;     for (int it = blockIdx.x; it < NIT; it += gridDim.x) {
;         int r = it;
;         if (r < I_IN) { tr_tile(p.in[9], 1024, 3856, r / 61, r % 61, tile, nullptr, (h16*)(ws + OFF_WT_IN), 1, (h16*)(ws + OFF_WT_G)); continue; } r -= I_IN;
_Z9hymba_fwd6Params:
	s_load_dwordx2 s[82:83], s[0:1], 0x100
	s_load_dword s33, s[0:1], 0x108
	s_add_u32 s24, s0, 0x108
	s_addc_u32 s25, s1, 0
	s_load_dwordx2 s[100:101], s[0:1], 0x48
	s_getreg_b32 s3, hwreg(HW_REG_XCC_ID, 0, 4)
	s_waitcnt lgkmcnt(0)
	s_add_u32 s4, s82, 0x1b6e900
	s_addc_u32 s5, s83, 0
	v_and_b32_e32 v240, 0x3ff, v0
	v_lshrrev_b32_e32 v241, 6, v240
	s_nop 1
	v_readfirstlane_b32 s97, v241
	s_cmp_gt_u32 s97, 2
	s_cbranch_scc1 .Lp0_nowarm
	s_lshl_b32 s98, s97, 8
	s_add_i32 s98, s98, s2
	s_addk_i32 s98, 0x100
	s_cmpk_gt_u32 s98, 0x3cf
	s_cbranch_scc1 .Lp0_nowarm
	s_mul_i32 s99, s98, 0x433
	s_lshr_b32 s99, s99, 16
	s_mul_i32 s97, s99, 61
	s_sub_i32 s98, s98, s97
	s_cmp_eq_u32 s98, 60
	s_cbranch_scc1 .Lp0_nowarm
	v_and_b32_e32 v240, 63, v240
	v_lshl_add_u32 v240, s99, 6, v240
	v_mul_u32_u24_e32 v240, 0x3c40, v240
	v_lshl_add_u32 v240, s98, 8, v240
	global_load_dword v241, v240, s[100:101]
	global_load_dword v242, v240, s[100:101] offset:128
	global_load_dword v243, v240, s[100:101] offset:252
.Lp0_nowarm:
	s_cmp_eq_u32 s2, 0
	v_writelane_b32 v253, s4, 0
	s_mov_b32 s8, 0
	s_cselect_b64 s[6:7], -1, 0
	s_cmp_lg_u32 s2, 0
	v_and_b32_e32 v132, 0x3ff, v0
	v_writelane_b32 v253, s5, 1
	s_cbranch_scc1 .LBB0_8
	v_cmp_eq_u32_e32 vcc, 0, v132
	s_and_saveexec_b64 s[98:99], vcc
	s_cbranch_execz .Lgs_init_done
	s_load_dwordx2 s[100:101], s[24:25], 0x58
	v_mov_b32_e32 v1, 0
	v_mov_b32_e32 v2, 0x3600
	global_store_dword v2, v1, s[4:5] offset:0 sc0 sc1
	global_store_dword v2, v1, s[4:5] offset:128 sc0 sc1
	global_store_dword v2, v1, s[4:5] offset:256 sc0 sc1
	global_store_dword v2, v1, s[4:5] offset:384 sc0 sc1
	global_store_dword v2, v1, s[4:5] offset:512 sc0 sc1
	global_store_dword v2, v1, s[4:5] offset:640 sc0 sc1
	global_store_dword v2, v1, s[4:5] offset:768 sc0 sc1
	global_store_dword v2, v1, s[4:5] offset:896 sc0 sc1
	global_store_dword v2, v1, s[4:5] offset:1024 sc0 sc1
	global_store_dword v2, v1, s[4:5] offset:1152 sc0 sc1
	global_store_dword v2, v1, s[4:5] offset:1280 sc0 sc1
	global_store_dword v2, v1, s[4:5] offset:1408 sc0 sc1
	global_store_dword v2, v1, s[4:5] offset:1536 sc0 sc1
	global_store_dword v2, v1, s[4:5] offset:1664 sc0 sc1
	global_store_dword v2, v1, s[4:5] offset:1792 sc0 sc1
	global_store_dword v2, v1, s[4:5] offset:1920 sc0 sc1
	global_store_dword v2, v1, s[4:5] offset:2048 sc0 sc1
	s_waitcnt vmcnt(0) lgkmcnt(0)
	v_mov_b32_e32 v2, 1
	global_atomic_add v1, v2, s[100:101] offset:32
